# M1: column-sum reads of waves 0-1 all issued first (adds keep their order)
# baseline (speedup 1.0000x reference)
.LBB0_374:
	s_or_b64 exec, exec, s[2:3]
	v_lshlrev_b32_e32 v60, 3, v2
	s_and_b32 s0, s20, 0x180
	v_and_b32_e32 v85, 0x78, v60
	s_lshl_b32 s0, s0, 2
	s_add_i32 s0, s0, 0
	v_lshlrev_b32_e32 v114, 2, v85
	v_add_u32_e32 v60, s0, v114
	v_add_u32_e32 v110, 0x10800, v60
	ds_read_b128 v[86:89], v110
	ds_read_b128 v[60:63], v110 offset:16
	ds_read_b128 v[90:93], v110 offset:4096
	ds_read_b128 v[94:97], v110 offset:8192
	ds_read_b128 v[98:101], v110 offset:12288
	v_lshlrev_b32_e32 v117, 16, v41
	v_and_b32_e32 v41, 0xffff0000, v41
	v_lshlrev_b32_e32 v115, 16, v57
	v_and_b32_e32 v57, 0xffff0000, v57
	s_waitcnt lgkmcnt(2)
	v_mul_f32_e32 v128, v93, v41
	v_lshlrev_b32_e32 v119, 16, v49
	v_and_b32_e32 v49, 0xffff0000, v49
	v_fmac_f32_e32 v128, v89, v57
	v_lshlrev_b32_e32 v121, 16, v53
	v_and_b32_e32 v53, 0xffff0000, v53
	s_waitcnt lgkmcnt(1)
	v_fmac_f32_e32 v128, v97, v49
	s_waitcnt lgkmcnt(0)
	v_fmac_f32_e32 v128, v101, v53
	v_mul_f32_e32 v57, 0xbfb8aa3b, v128
	v_exp_f32_e32 v57, v57
	v_lshlrev_b32_e32 v116, 16, v40
	v_and_b32_e32 v40, 0xffff0000, v40
	v_lshlrev_b32_e32 v118, 16, v48
	v_lshlrev_b32_e32 v106, 16, v56
	v_and_b32_e32 v56, 0xffff0000, v56
	v_mul_f32_e32 v123, v90, v116
	v_mul_f32_e32 v126, v91, v40
	v_add_f32_e32 v57, 1.0, v57
	v_mul_f32_e32 v90, v90, v118
	v_and_b32_e32 v48, 0xffff0000, v48
	v_lshlrev_b32_e32 v120, 16, v52
	v_fmac_f32_e32 v126, v87, v56
	v_rcp_f32_e32 v57, v57
	v_fmac_f32_e32 v90, v86, v116
	v_lshlrev_b32_e32 v122, 16, v44
	v_fmac_f32_e32 v126, v95, v48
	v_fmac_f32_e32 v90, v94, v120
	v_mul_f32_e32 v48, v91, v48
	v_and_b32_e32 v52, 0xffff0000, v52
	v_fmac_f32_e32 v90, v98, v122
	v_fmac_f32_e32 v48, v87, v40
	v_fmac_f32_e32 v123, v86, v106
	v_and_b32_e32 v44, 0xffff0000, v44
	v_mul_f32_e32 v86, 0xbfb8aa3b, v90
	v_fmac_f32_e32 v48, v95, v52
	v_exp_f32_e32 v86, v86
	v_fmac_f32_e32 v48, v99, v44
	v_mul_f32_e32 v44, v128, v57
	v_mul_f32_e32 v57, v92, v119
	v_fmac_f32_e32 v57, v88, v117
	v_lshlrev_b32_e32 v125, 16, v45
	v_fmac_f32_e32 v57, v96, v121
	v_fmac_f32_e32 v57, v100, v125
	v_fmac_f32_e32 v126, v99, v52
	v_add_f32_e32 v52, 1.0, v86
	v_mul_f32_e32 v86, 0xbfb8aa3b, v57
	v_exp_f32_e32 v86, v86
	v_mul_f32_e32 v49, v93, v49
	v_fmac_f32_e32 v49, v89, v41
	v_and_b32_e32 v45, 0xffff0000, v45
	v_fmac_f32_e32 v49, v97, v53
	v_fmac_f32_e32 v49, v101, v45
	v_add_f32_e32 v45, 1.0, v86
	ds_read_b128 v[102:105], v110 offset:4112
	ds_read_b128 v[106:109], v110 offset:8208
	v_rcp_f32_e32 v45, v45
	v_mul_f32_e32 v40, 0xbfb8aa3b, v48
	v_mul_f32_e32 v41, 0xbfb8aa3b, v49
	v_exp_f32_e32 v40, v40
	v_exp_f32_e32 v41, v41
	ds_read_b128 v[110:113], v110 offset:12304
	v_mul_f32_e32 v45, v57, v45
	v_lshlrev_b32_e32 v53, 16, v59
	v_and_b32_e32 v57, 0xffff0000, v59
	v_lshlrev_b32_e32 v59, 16, v43
	v_and_b32_e32 v43, 0xffff0000, v43
	s_waitcnt lgkmcnt(2)
	v_mul_f32_e32 v95, v105, v43
	v_add_f32_e32 v40, 1.0, v40
	v_add_f32_e32 v41, 1.0, v41
	v_lshlrev_b32_e32 v87, 16, v51
	v_and_b32_e32 v51, 0xffff0000, v51
	v_fmac_f32_e32 v95, v63, v57
	v_rcp_f32_e32 v40, v40
	v_rcp_f32_e32 v41, v41
	v_lshlrev_b32_e32 v89, 16, v55
	v_and_b32_e32 v55, 0xffff0000, v55
	s_waitcnt lgkmcnt(1)
	v_fmac_f32_e32 v95, v109, v51
	s_waitcnt lgkmcnt(0)
	v_fmac_f32_e32 v95, v113, v55
	v_mul_f32_e32 v57, 0xbfb8aa3b, v95
	v_exp_f32_e32 v57, v57
	v_mul_f32_e32 v40, v48, v40
	v_mul_f32_e32 v41, v49, v41
	v_lshlrev_b32_e32 v48, 16, v58
	v_and_b32_e32 v49, 0xffff0000, v58
	v_lshlrev_b32_e32 v58, 16, v42
	v_rcp_f32_e32 v52, v52
	v_mul_f32_e32 v91, v102, v58
	v_and_b32_e32 v42, 0xffff0000, v42
	v_lshlrev_b32_e32 v86, 16, v50
	v_fmac_f32_e32 v91, v60, v48
	v_mul_f32_e32 v127, v92, v117
	v_fmac_f32_e32 v91, v106, v86
	v_mul_f32_e32 v93, v103, v42
	v_add_f32_e32 v57, 1.0, v57
	v_mul_f32_e32 v86, v102, v86
	v_fmac_f32_e32 v127, v88, v115
	v_and_b32_e32 v50, 0xffff0000, v50
	v_lshlrev_b32_e32 v88, 16, v54
	v_fmac_f32_e32 v93, v61, v49
	v_rcp_f32_e32 v57, v57
	v_fmac_f32_e32 v86, v60, v58
	v_mul_f32_e32 v52, v90, v52
	v_lshlrev_b32_e32 v90, 16, v46
	v_fmac_f32_e32 v93, v107, v50
	v_fmac_f32_e32 v86, v106, v88
	v_mul_f32_e32 v50, v103, v50
	v_and_b32_e32 v54, 0xffff0000, v54
	v_fmac_f32_e32 v86, v110, v90
	v_fmac_f32_e32 v50, v61, v42
	v_and_b32_e32 v46, 0xffff0000, v46
	v_mul_f32_e32 v58, 0xbfb8aa3b, v86
	v_fmac_f32_e32 v50, v107, v54
	v_exp_f32_e32 v58, v58
	v_fmac_f32_e32 v50, v111, v46
	v_mul_f32_e32 v46, v95, v57
	v_mul_f32_e32 v57, v104, v87
	v_fmac_f32_e32 v57, v62, v59
	v_fmac_f32_e32 v123, v94, v118
	v_lshlrev_b32_e32 v92, 16, v47
	v_fmac_f32_e32 v57, v108, v89
	v_fmac_f32_e32 v123, v98, v120
	v_fmac_f32_e32 v57, v112, v92
	v_mul_f32_e32 v124, 0xbfb8aa3b, v123
	v_fmac_f32_e32 v93, v111, v54
	v_add_f32_e32 v54, 1.0, v58
	v_mul_f32_e32 v58, 0xbfb8aa3b, v57
	v_exp_f32_e32 v124, v124
	v_exp_f32_e32 v58, v58
	v_mul_f32_e32 v42, 0xbfb8aa3b, v50
	v_mul_f32_e32 v51, v105, v51
	v_ashrrev_i32_e32 v84, 4, v2
	v_mul_f32_e32 v56, 0xbfb8aa3b, v126
	v_mul_f32_e32 v94, v104, v59
	v_exp_f32_e32 v42, v42
	v_fmac_f32_e32 v51, v63, v43
	v_exp_f32_e32 v56, v56
	v_fmac_f32_e32 v127, v96, v119
	v_and_b32_e32 v47, 0xffff0000, v47
	v_fmac_f32_e32 v94, v62, v53
	v_fmac_f32_e32 v51, v109, v55
	v_lshl_add_u32 v62, v84, 3, 0
	v_add_f32_e32 v124, 1.0, v124
	v_fmac_f32_e32 v127, v100, v121
	v_fmac_f32_e32 v51, v113, v47
	v_add_f32_e32 v47, 1.0, v58
	v_lshlrev_b32_e32 v58, 16, v32
	v_and_b32_e32 v59, 0xffff0000, v32
	v_lshlrev_b32_e32 v60, 16, v33
	v_and_b32_e32 v61, 0xffff0000, v33
	s_barrier
	ds_read_b64 v[32:33], v62 offset:36864
	v_mul_f32_e32 v115, 0xbfb8aa3b, v127
	v_rcp_f32_e32 v124, v124
	v_exp_f32_e32 v115, v115
	v_add_f32_e32 v42, 1.0, v42
	v_add_f32_e32 v56, 1.0, v56
	v_rcp_f32_e32 v42, v42
	v_rcp_f32_e32 v56, v56
	v_mul_f32_e32 v43, 0xbfb8aa3b, v51
	v_mul_f32_e32 v123, v123, v124
	v_fmac_f32_e32 v94, v108, v87
	v_exp_f32_e32 v43, v43
	s_waitcnt lgkmcnt(0)
	v_mul_f32_e32 v32, 0x3db504f3, v32
	v_mul_f32_e32 v33, 0x3db504f3, v33
	v_lshlrev_b32_e32 v87, 2, v84
	v_add_f32_e32 v115, 1.0, v115
	v_fmac_f32_e32 v91, v110, v88
	v_fmac_f32_e32 v94, v112, v89
	v_sub_u32_e32 v62, v62, v87
	v_lshlrev_b32_e32 v87, 9, v84
	v_mul_f32_e32 v88, v123, v32
	v_mul_f32_e32 v52, v52, v33
	v_mul_u32_u24_e32 v89, 0x48, v85
	v_rcp_f32_e32 v115, v115
	v_mul_f32_e32 v48, 0xbfb8aa3b, v91
	v_mul_f32_e32 v42, v50, v42
	v_lshlrev_b32_e32 v50, 16, v36
	v_add3_u32 v87, 0, v114, v87
	v_cvt_pk_bf16_f32 v88, v88, v52
	v_lshl_add_u32 v62, v89, 1, v62
	v_fmac_f32_e32 v52, v123, v32
	v_mul_f32_e32 v56, v126, v56
	v_exp_f32_e32 v48, v48
	ds_write_b32 v62, v88
	ds_write_b32 v87, v52 offset:37120
	v_cvt_pk_bf16_f32 v50, v50, v58
	v_add_f32_e32 v43, 1.0, v43
	ds_write_b32 v62, v50 offset:18432
	v_mul_f32_e32 v50, v56, v32
	v_mul_f32_e32 v40, v40, v33
	v_mul_f32_e32 v49, 0xbfb8aa3b, v93
	v_rcp_f32_e32 v43, v43
	v_and_b32_e32 v36, 0xffff0000, v36
	v_cvt_pk_bf16_f32 v50, v50, v40
	v_fmac_f32_e32 v40, v56, v32
	v_mul_f32_e32 v115, v127, v115
	v_exp_f32_e32 v49, v49
	ds_write_b32 v62, v50 offset:144
	ds_write_b32 v87, v40 offset:37124
	v_cvt_pk_bf16_f32 v36, v36, v59
	v_add_f32_e32 v48, 1.0, v48
	ds_write_b32 v62, v36 offset:18576
	v_mul_f32_e32 v36, v115, v32
	v_mul_f32_e32 v40, v45, v33
	v_mul_f32_e32 v53, 0xbfb8aa3b, v94
	v_rcp_f32_e32 v48, v48
	v_rcp_f32_e32 v54, v54
	v_cvt_pk_bf16_f32 v36, v36, v40
	v_fmac_f32_e32 v40, v115, v32
	v_exp_f32_e32 v53, v53
	v_mul_f32_e32 v43, v51, v43
	v_lshlrev_b32_e32 v51, 16, v37
	ds_write_b32 v62, v36 offset:288
	ds_write_b32 v87, v40 offset:37128
	v_cvt_pk_bf16_f32 v36, v51, v60
	v_add_f32_e32 v49, 1.0, v49
	ds_write_b32 v62, v36 offset:18720
	v_mul_f32_e32 v36, v44, v32
	v_mul_f32_e32 v40, v41, v33
	v_rcp_f32_e32 v49, v49
	v_cvt_pk_bf16_f32 v36, v36, v40
	v_fmac_f32_e32 v40, v44, v32
	v_mul_f32_e32 v48, v91, v48
	v_mul_f32_e32 v54, v86, v54
	v_and_b32_e32 v37, 0xffff0000, v37
	ds_write_b32 v62, v36 offset:432
	ds_write_b32 v87, v40 offset:37132
	v_cvt_pk_bf16_f32 v36, v37, v61
	v_add_f32_e32 v53, 1.0, v53
	ds_write_b32 v62, v36 offset:18864
	v_mul_f32_e32 v36, v32, v48
	v_mul_f32_e32 v37, v33, v54
	v_rcp_f32_e32 v53, v53
	v_rcp_f32_e32 v47, v47
	v_cvt_pk_bf16_f32 v36, v36, v37
	v_fmac_f32_e32 v37, v32, v48
	v_mul_f32_e32 v49, v93, v49
	v_lshlrev_b32_e32 v55, 16, v38
	v_lshlrev_b32_e32 v63, 16, v34
	ds_write_b32 v62, v36 offset:576
	ds_write_b32 v87, v37 offset:37136
	v_cvt_pk_bf16_f32 v36, v55, v63
	ds_write_b32 v62, v36 offset:19008
	v_mul_f32_e32 v36, v32, v49
	v_mul_f32_e32 v37, v33, v42
	v_and_b32_e32 v34, 0xffff0000, v34
	v_cvt_pk_bf16_f32 v36, v36, v37
	v_fmac_f32_e32 v37, v32, v49
	v_mul_f32_e32 v53, v94, v53
	v_mul_f32_e32 v47, v57, v47
	v_and_b32_e32 v38, 0xffff0000, v38
	ds_write_b32 v62, v36 offset:720
	ds_write_b32 v87, v37 offset:37140
	v_cvt_pk_bf16_f32 v34, v38, v34
	ds_write_b32 v62, v34 offset:19152
	v_mul_f32_e32 v34, v32, v53
	v_mul_f32_e32 v36, v33, v47
	v_cvt_pk_bf16_f32 v34, v34, v36
	v_fmac_f32_e32 v36, v32, v53
	v_lshlrev_b32_e32 v57, 16, v39
	v_lshlrev_b32_e32 v86, 16, v35
	ds_write_b32 v62, v34 offset:864
	ds_write_b32 v87, v36 offset:37144
	v_cvt_pk_bf16_f32 v34, v57, v86
	ds_write_b32 v62, v34 offset:19296
	v_mul_f32_e32 v34, v32, v46
	v_mul_f32_e32 v33, v33, v43
	v_cvt_pk_bf16_f32 v34, v34, v33
	v_fmac_f32_e32 v33, v32, v46
	v_cmp_lt_i32_e64 s[0:1], s35, v2
	v_and_b32_e32 v39, 0xffff0000, v39
	v_and_b32_e32 v35, 0xffff0000, v35
	ds_write_b32 v62, v34 offset:1008
	ds_write_b32 v87, v33 offset:37148
	v_cvt_pk_bf16_f32 v32, v39, v35
	ds_write_b32 v62, v32 offset:19440
	s_waitcnt lgkmcnt(0)
	s_barrier
	s_and_saveexec_b64 s[28:29], s[0:1]
	s_xor_b64 s[0:1], exec, s[28:29]
	s_bfe_i64 s[2:3], s[22:23], 0x200000
	s_or_saveexec_b64 s[0:1], s[0:1]
	v_mov_b64_e32 v[32:33], s[2:3]
	s_xor_b64 exec, exec, s[0:1]
	s_cbranch_execz .LBB0_360
	ds_read2st64_b32 v[130:131], v3 offset0:145 offset1:147
	ds_read2st64_b32 v[132:133], v3 offset0:149 offset1:151
	ds_read2st64_b32 v[134:135], v3 offset0:153 offset1:155
	ds_read2st64_b32 v[136:137], v3 offset0:157 offset1:159
	ds_read2st64_b32 v[138:139], v3 offset0:161 offset1:163
	ds_read2st64_b32 v[140:141], v3 offset0:165 offset1:167
	ds_read2st64_b32 v[142:143], v3 offset0:169 offset1:171
	ds_read2st64_b32 v[144:145], v3 offset0:173 offset1:175
	ds_read2st64_b32 v[146:147], v3 offset0:177 offset1:179
	ds_read2st64_b32 v[148:149], v3 offset0:181 offset1:183
	ds_read2st64_b32 v[150:151], v3 offset0:185 offset1:187
	ds_read2st64_b32 v[152:153], v3 offset0:189 offset1:191
	ds_read2st64_b32 v[154:155], v3 offset0:193 offset1:195
	ds_read2st64_b32 v[156:157], v3 offset0:197 offset1:199
	ds_read2st64_b32 v[158:159], v3 offset0:201 offset1:203
	ds_read2st64_b32 v[160:161], v3 offset0:205 offset1:207
	s_waitcnt lgkmcnt(15)
	v_add_f32_e32 v34, 0, v130
	v_add_f32_e32 v34, v34, v131
	s_waitcnt lgkmcnt(14)
	v_add_f32_e32 v34, v34, v132
	v_add_f32_e32 v34, v34, v133
	s_waitcnt lgkmcnt(13)
	v_add_f32_e32 v34, v34, v134
	v_add_f32_e32 v34, v34, v135
	s_waitcnt lgkmcnt(12)
	v_add_f32_e32 v34, v34, v136
	v_add_f32_e32 v34, v34, v137
	s_waitcnt lgkmcnt(11)
	v_add_f32_e32 v34, v34, v138
	v_add_f32_e32 v34, v34, v139
	s_waitcnt lgkmcnt(10)
	v_add_f32_e32 v34, v34, v140
	v_add_f32_e32 v34, v34, v141
	s_waitcnt lgkmcnt(9)
	v_add_f32_e32 v34, v34, v142
	v_add_f32_e32 v34, v34, v143
	s_waitcnt lgkmcnt(8)
	v_add_f32_e32 v34, v34, v144
	v_add_f32_e32 v34, v34, v145
	s_waitcnt lgkmcnt(7)
	v_add_f32_e32 v34, v34, v146
	v_add_f32_e32 v34, v34, v147
	s_waitcnt lgkmcnt(6)
	v_add_f32_e32 v34, v34, v148
	v_add_f32_e32 v34, v34, v149
	s_waitcnt lgkmcnt(5)
	v_add_f32_e32 v34, v34, v150
	v_add_f32_e32 v34, v34, v151
	s_waitcnt lgkmcnt(4)
	v_add_f32_e32 v34, v34, v152
	v_add_f32_e32 v34, v34, v153
	s_waitcnt lgkmcnt(3)
	v_add_f32_e32 v34, v34, v154
	v_add_f32_e32 v34, v34, v155
	s_waitcnt lgkmcnt(2)
	v_add_f32_e32 v34, v34, v156
	v_add_f32_e32 v34, v34, v157
	s_waitcnt lgkmcnt(1)
	v_add_f32_e32 v34, v34, v158
	v_add_f32_e32 v34, v34, v159
	s_waitcnt lgkmcnt(0)
	v_add_f32_e32 v34, v34, v160
	v_add_f32_e32 v34, v34, v161
	v_ashrrev_i32_e32 v3, 31, v2
	v_lshl_add_u64 v[32:33], v[2:3], 2, s[24:25]
	global_store_dword v[32:33], v34, off
	v_mov_b64_e32 v[32:33], s[22:23]
	s_branch .LBB0_360
